# mix-phase deferred weight-transpose jobs: 16 serialized load->wait->ds_write ladders turned into 16 loads in flight with counted waits (3 loops)
# speedup vs baseline: 1.0033x; 1.0033x over previous
; __device__ void transpose_job64(int tid_, int bid_, int nblk_, const float* __restrict__ src, u16* __restrict__ dst, int K, int N,
;                                 int nbatch, size_t sstride, size_t dstride, int ldd, float* sm) {
;     ...
;   for (int t = bid_; t < total; t += nblk_) {
;     int bi = t / per, r = t % per, kt = r / tn, nt = r % tn;
;     const float* s = src + (size_t)bi * sstride + (size_t)(kt * 64) * N + nt * 64;
; #pragma unroll
;     for (int i = 0; i < 16; ++i) {
;       int kk = (tid >> 6) + 4 * i, nn = tid & 63;
;       sm[kk * 65 + nn] = s[(size_t)kk * N + nn];
;     }
;     __syncthreads();
; __device__ void mix_phase(int tid_, int bid_, int nblk_, const Params& p, int li, char* smem) {
;     ...
;     if (j < 160) { transpose_job64(tid_, j, 160, p.od_w_out, p.wt_od_out, DC, 2048, 2, (size_t)DC * 2048, (size_t)DC * 2048, DC, sm); continue; }
.LBB0_615:
	s_mul_hi_i32 s20, s0, 0x66666667
	s_lshr_b32 s21, s20, 31
	s_ashr_i32 s20, s20, 9
	s_add_i32 s20, s20, s21
	s_mul_i32 s21, s20, 0xfffffb00
	s_add_i32 s21, s0, s21
	s_bfe_u32 s22, s21, 0x5001a
	s_add_i32 s22, s21, s22
	s_sext_i32_i16 s24, s22
	s_and_b32 s22, s22, 0xffe0
	s_sub_i32 s21, s21, s22
	s_sext_i32_i16 s26, s21
	s_mul_hi_i32 s21, s20, 0x500000
	s_mul_i32 s20, s20, 0x500000
	s_lshl_b64 s[22:23], s[20:21], 2
	s_add_u32 s27, s46, s22
	s_addc_u32 s28, s47, s23
	s_lshl_b32 s22, s24, 1
	s_andn2_b32 s22, s22, 63
	s_ashr_i32 s23, s22, 31
	s_lshl_b64 s[24:25], s[22:23], 13
	s_add_u32 s29, s27, s24
	s_addc_u32 s28, s28, s25
	s_lshl_b32 s24, s26, 6
	s_ashr_i32 s25, s24, 31
	s_lshl_b64 s[26:27], s[24:25], 2
	s_add_u32 s26, s29, s26
	s_addc_u32 s27, s28, s27
	v_lshlrev_b32_e32 v2, 2, v52
	v_mov_b32_e32 v3, v0
	v_lshl_add_u64 v[2:3], s[26:27], 0, v[2:3]
	v_lshl_add_u64 v[4:5], v[2:3], 0, v[56:57]
	global_load_dword v22, v[4:5], off
	v_lshl_add_u64 v[4:5], v[2:3], 0, v[58:59]
	s_lshl_b64 s[20:21], s[20:21], 1
	s_add_u32 s20, s8, s20
	s_addc_u32 s21, s9, s21
	v_mov_b64_e32 v[18:19], s[20:21]
	v_lshlrev_b32_e32 v20, 1, v54
	v_mov_b32_e32 v21, v0
	global_load_dword v23, v[4:5], off
	v_lshl_add_u64 v[4:5], v[2:3], 0, v[60:61]
	global_load_dword v24, v[4:5], off
	v_lshl_add_u64 v[4:5], v[2:3], 0, v[62:63]
	global_load_dword v25, v[4:5], off
	v_lshl_add_u64 v[4:5], v[2:3], 0, v[64:65]
	global_load_dword v26, v[4:5], off
	v_lshl_add_u64 v[4:5], v[2:3], 0, v[66:67]
	global_load_dword v27, v[4:5], off
	v_lshl_add_u64 v[4:5], v[2:3], 0, v[68:69]
	global_load_dword v28, v[4:5], off
	v_lshl_add_u64 v[4:5], v[2:3], 0, v[70:71]
	global_load_dword v29, v[4:5], off
	v_lshl_add_u64 v[4:5], v[2:3], 0, v[72:73]
	global_load_dword v30, v[4:5], off
	v_lshl_add_u64 v[4:5], v[2:3], 0, v[74:75]
	global_load_dword v31, v[4:5], off
	v_lshl_add_u64 v[4:5], v[2:3], 0, v[76:77]
	global_load_dword v32, v[4:5], off
	v_lshl_add_u64 v[4:5], v[2:3], 0, v[78:79]
	global_load_dword v33, v[4:5], off
	v_lshl_add_u64 v[4:5], v[2:3], 0, v[80:81]
	global_load_dword v34, v[4:5], off
	v_lshl_add_u64 v[4:5], v[2:3], 0, v[82:83]
	global_load_dword v35, v[4:5], off
	v_lshl_add_u64 v[4:5], v[2:3], 0, v[84:85]
	v_lshl_add_u64 v[2:3], v[2:3], 0, v[86:87]
	global_load_dword v36, v[4:5], off
	global_load_dword v37, v[2:3], off
	v_add_u32_e32 v6, v182, v185
	s_waitcnt vmcnt(15)
	ds_write_b32 v6, v22
	s_waitcnt vmcnt(14)
	ds_write_b32 v6, v23 offset:1040
	s_waitcnt vmcnt(13)
	ds_write_b32 v6, v24 offset:2080
	s_waitcnt vmcnt(12)
	ds_write_b32 v6, v25 offset:3120
	s_waitcnt vmcnt(11)
	ds_write_b32 v6, v26 offset:4160
	s_waitcnt vmcnt(10)
	ds_write_b32 v6, v27 offset:5200
	v_add_u32_e32 v6, v182, v186
	s_waitcnt vmcnt(9)
	ds_write_b32 v6, v28
	s_waitcnt vmcnt(8)
	ds_write_b32 v6, v29 offset:1040
	s_waitcnt vmcnt(7)
	ds_write_b32 v6, v30 offset:2080
	s_waitcnt vmcnt(6)
	ds_write_b32 v6, v31 offset:3120
	s_waitcnt vmcnt(5)
	ds_write_b32 v6, v32 offset:4160
	s_waitcnt vmcnt(4)
	ds_write_b32 v6, v33 offset:5200
	s_waitcnt vmcnt(3)
	ds_write_b32 v6, v34 offset:6240
	s_waitcnt vmcnt(2)
	ds_write_b32 v6, v35 offset:7280
	s_waitcnt vmcnt(1)
	ds_write_b32 v6, v36 offset:8320
	s_waitcnt vmcnt(0)
	ds_write_b32 v6, v37 offset:9360
	s_waitcnt lgkmcnt(0)
	s_barrier
; __device__ __forceinline__ unsigned pack2(float a, float b) { return (unsigned)f2bf(a) | ((unsigned)f2bf(b) << 16); }
; __device__ void transpose_job64(int tid_, int bid_, int nblk_, const float* __restrict__ src, u16* __restrict__ dst, int K, int N,
;                                 int nbatch, size_t sstride, size_t dstride, int ldd, float* sm) {
;     ...
;     {
;       int n = tid >> 2, kc = tid & 3;
;       unsigned o[8];
; #pragma unroll
;       for (int e = 0; e < 8; ++e) o[e] = pack2(sm[(kc * 16 + 2 * e) * 65 + n], sm[(kc * 16 + 2 * e + 1) * 65 + n]);
;       u16* d = dst + (size_t)bi * dstride + (size_t)(nt * 64 + n) * ldd + kt * 64 + kc * 16;
;       *(uint4*)(d) = make_uint4(o[0], o[1], o[2], o[3]);
;       *(uint4*)(d + 8) = make_uint4(o[4], o[5], o[6], o[7]);
;     }
;     __syncthreads();
	ds_read2_b32 v[2:3], v184 offset1:65
	ds_read2_b32 v[4:5], v184 offset0:130 offset1:195
	v_add_u32_e32 v1, 0x400, v184
	ds_read2_b32 v[6:7], v1 offset0:4 offset1:69
	ds_read2_b32 v[8:9], v1 offset0:134 offset1:199
	v_add_u32_e32 v1, 0x800, v184
	ds_read2_b32 v[10:11], v1 offset0:8 offset1:73
	ds_read2_b32 v[12:13], v1 offset0:138 offset1:203
	v_add_u32_e32 v1, 0xc00, v184
	ds_read2_b32 v[14:15], v1 offset0:12 offset1:77
	ds_read2_b32 v[16:17], v1 offset0:142 offset1:207
	v_add_u32_e32 v1, s24, v183
	v_mad_i64_i32 v[18:19], s[20:21], v1, s89, v[18:19]
	v_lshl_add_u64 v[18:19], s[22:23], 1, v[18:19]
	s_waitcnt lgkmcnt(6)
	v_and_b32_sdwa v1, v4, v198 dst_sel:DWORD dst_unused:UNUSED_PAD src0_sel:WORD_1 src1_sel:DWORD
	v_lshl_add_u64 v[18:19], v[18:19], 0, v[20:21]
	v_and_b32_sdwa v20, v2, v198 dst_sel:DWORD dst_unused:UNUSED_PAD src0_sel:WORD_1 src1_sel:DWORD
	v_add3_u32 v1, v4, v1, s63
	v_and_b32_sdwa v4, v5, v198 dst_sel:DWORD dst_unused:UNUSED_PAD src0_sel:WORD_1 src1_sel:DWORD
	v_add3_u32 v2, v2, v20, s63
	v_and_b32_sdwa v20, v3, v198 dst_sel:DWORD dst_unused:UNUSED_PAD src0_sel:WORD_1 src1_sel:DWORD
	v_add3_u32 v4, v5, v4, s63
	v_add3_u32 v3, v3, v20, s63
	v_and_b32_e32 v4, 0xffff0000, v4
	v_and_b32_e32 v5, 0xffff0000, v3
	v_or_b32_sdwa v3, v4, v1 dst_sel:DWORD dst_unused:UNUSED_PAD src0_sel:DWORD src1_sel:WORD_1
	s_waitcnt lgkmcnt(5)
	v_and_b32_sdwa v4, v6, v198 dst_sel:DWORD dst_unused:UNUSED_PAD src0_sel:WORD_1 src1_sel:DWORD
	v_or_b32_sdwa v2, v5, v2 dst_sel:DWORD dst_unused:UNUSED_PAD src0_sel:DWORD src1_sel:WORD_1
	v_add3_u32 v4, v6, v4, s63
	s_waitcnt lgkmcnt(4)
	v_and_b32_sdwa v5, v9, v198 dst_sel:DWORD dst_unused:UNUSED_PAD src0_sel:WORD_1 src1_sel:DWORD
	v_and_b32_sdwa v6, v7, v198 dst_sel:DWORD dst_unused:UNUSED_PAD src0_sel:WORD_1 src1_sel:DWORD
	v_and_b32_sdwa v1, v8, v198 dst_sel:DWORD dst_unused:UNUSED_PAD src0_sel:WORD_1 src1_sel:DWORD
	v_add3_u32 v5, v9, v5, s63
	v_add3_u32 v6, v7, v6, s63
	v_add3_u32 v1, v8, v1, s63
	v_and_b32_e32 v5, 0xffff0000, v5
	v_and_b32_e32 v6, 0xffff0000, v6
	v_or_b32_sdwa v5, v5, v1 dst_sel:DWORD dst_unused:UNUSED_PAD src0_sel:DWORD src1_sel:WORD_1
	v_or_b32_sdwa v4, v6, v4 dst_sel:DWORD dst_unused:UNUSED_PAD src0_sel:DWORD src1_sel:WORD_1
	global_store_dwordx4 v[18:19], v[2:5], off
	s_waitcnt lgkmcnt(2)
	v_and_b32_sdwa v1, v12, v198 dst_sel:DWORD dst_unused:UNUSED_PAD src0_sel:WORD_1 src1_sel:DWORD
	v_add3_u32 v1, v12, v1, s63
	v_and_b32_sdwa v3, v13, v198 dst_sel:DWORD dst_unused:UNUSED_PAD src0_sel:WORD_1 src1_sel:DWORD
	v_and_b32_sdwa v4, v11, v198 dst_sel:DWORD dst_unused:UNUSED_PAD src0_sel:WORD_1 src1_sel:DWORD
	v_and_b32_sdwa v2, v10, v198 dst_sel:DWORD dst_unused:UNUSED_PAD src0_sel:WORD_1 src1_sel:DWORD
	v_add3_u32 v3, v13, v3, s63
	v_add3_u32 v4, v11, v4, s63
	v_add3_u32 v2, v10, v2, s63
	v_and_b32_e32 v3, 0xffff0000, v3
	v_and_b32_e32 v4, 0xffff0000, v4
	s_waitcnt lgkmcnt(0)
	v_and_b32_sdwa v5, v17, v198 dst_sel:DWORD dst_unused:UNUSED_PAD src0_sel:WORD_1 src1_sel:DWORD
	v_and_b32_sdwa v6, v15, v198 dst_sel:DWORD dst_unused:UNUSED_PAD src0_sel:WORD_1 src1_sel:DWORD
	v_or_b32_sdwa v3, v3, v1 dst_sel:DWORD dst_unused:UNUSED_PAD src0_sel:DWORD src1_sel:WORD_1
	v_or_b32_sdwa v2, v4, v2 dst_sel:DWORD dst_unused:UNUSED_PAD src0_sel:DWORD src1_sel:WORD_1
	v_and_b32_sdwa v1, v16, v198 dst_sel:DWORD dst_unused:UNUSED_PAD src0_sel:WORD_1 src1_sel:DWORD
	v_and_b32_sdwa v4, v14, v198 dst_sel:DWORD dst_unused:UNUSED_PAD src0_sel:WORD_1 src1_sel:DWORD
	v_add3_u32 v5, v17, v5, s63
	v_add3_u32 v6, v15, v6, s63
	v_add3_u32 v4, v14, v4, s63
	v_add3_u32 v1, v16, v1, s63
	v_and_b32_e32 v5, 0xffff0000, v5
	v_and_b32_e32 v6, 0xffff0000, v6
	s_add_i32 s20, s0, 0xa0
	v_or_b32_sdwa v5, v5, v1 dst_sel:DWORD dst_unused:UNUSED_PAD src0_sel:DWORD src1_sel:WORD_1
	v_or_b32_sdwa v4, v6, v4 dst_sel:DWORD dst_unused:UNUSED_PAD src0_sel:DWORD src1_sel:WORD_1
	s_cmpk_gt_i32 s0, 0x95f
	s_mov_b32 s0, s20
	global_store_dwordx4 v[18:19], v[2:5], off offset:16
	s_barrier
	s_cbranch_scc0 .LBB0_615
	s_mov_b64 s[20:21], 0

; __device__ void transpose_job64(int tid_, int bid_, int nblk_, const float* __restrict__ src, u16* __restrict__ dst, int K, int N,
;                                 int nbatch, size_t sstride, size_t dstride, int ldd, float* sm) {
;     ...
;   for (int t = bid_; t < total; t += nblk_) {
;     int bi = t / per, r = t % per, kt = r / tn, nt = r % tn;
;     const float* s = src + (size_t)bi * sstride + (size_t)(kt * 64) * N + nt * 64;
; #pragma unroll
;     for (int i = 0; i < 16; ++i) {
;       int kk = (tid >> 6) + 4 * i, nn = tid & 63;
;       sm[kk * 65 + nn] = s[(size_t)kk * N + nn];
;     }
;     __syncthreads();
; __device__ void mix_phase(int tid_, int bid_, int nblk_, const Params& p, int li, char* smem) {
;     ...
;     if (j < 320) { transpose_job64(tid_, j, 320, p.od_w_in, p.wt_od_in, 2048, OD_IN, 2, (size_t)2048 * OD_IN, (size_t)2048 * OD_IN, 2048, sm); continue; }
.LBB0_620:
	s_mul_hi_i32 s20, s0, 0x66666667
	s_lshr_b32 s21, s20, 31
	s_ashr_i32 s20, s20, 10
	s_add_i32 s20, s20, s21
	s_mul_i32 s21, s20, 0xfffff600
	s_add_i32 s21, s0, s21
	s_mul_i32 s22, s21, 0x6667
	s_lshr_b32 s23, s22, 31
	s_ashr_i32 s22, s22, 21
	s_add_i32 s24, s22, s23
	s_mul_i32 s22, s24, 0x50
	s_sub_i32 s21, s21, s22
	s_mul_hi_i32 s23, s20, 0xa00000
	s_mul_i32 s22, s20, 0xa00000
	s_sext_i32_i16 s25, s21
	s_lshl_b64 s[20:21], s[22:23], 2
	s_add_u32 s26, s46, s20
	s_addc_u32 s27, s47, s21
	s_lshl_b32 s20, s24, 6
	s_ashr_i32 s21, s20, 31
	s_mul_i32 s24, s24, 0x140000
	s_mul_hi_i32 s28, s20, 0x5000
	s_add_u32 s29, s26, s24
	s_addc_u32 s28, s27, s28
	s_lshl_b32 s24, s25, 6
	s_ashr_i32 s25, s24, 31
	s_lshl_b64 s[26:27], s[24:25], 2
	s_add_u32 s26, s29, s26
	s_addc_u32 s27, s28, s27
	v_lshlrev_b32_e32 v2, 2, v52
	v_mov_b32_e32 v3, v0
	v_lshl_add_u64 v[2:3], s[26:27], 0, v[2:3]
	v_lshl_add_u64 v[4:5], v[2:3], 0, v[88:89]
	global_load_dword v22, v[4:5], off
	v_lshl_add_u64 v[4:5], v[2:3], 0, v[90:91]
	s_lshl_b64 s[22:23], s[22:23], 1
	v_add_u32_e32 v18, s24, v183
	s_add_u32 s22, s6, s22
	v_ashrrev_i32_e32 v19, 31, v18
	s_addc_u32 s23, s7, s23
	v_lshlrev_b64 v[18:19], 12, v[18:19]
	v_lshl_add_u64 v[18:19], s[22:23], 0, v[18:19]
	v_lshl_add_u64 v[18:19], s[20:21], 1, v[18:19]
	v_lshlrev_b32_e32 v20, 1, v54
	v_mov_b32_e32 v21, v0
	v_lshl_add_u64 v[18:19], v[18:19], 0, v[20:21]
	s_add_i32 s20, s0, 0x140
	s_cmpk_gt_i32 s0, 0x12bf
	s_mov_b32 s0, s20
	global_load_dword v23, v[4:5], off
	v_lshl_add_u64 v[4:5], v[2:3], 0, v[92:93]
	global_load_dword v24, v[4:5], off
	v_lshl_add_u64 v[4:5], v[2:3], 0, v[94:95]
	global_load_dword v25, v[4:5], off
	v_lshl_add_u64 v[4:5], v[2:3], 0, v[96:97]
	global_load_dword v26, v[4:5], off
	v_lshl_add_u64 v[4:5], v[2:3], 0, v[98:99]
	global_load_dword v27, v[4:5], off
	v_lshl_add_u64 v[4:5], v[2:3], 0, v[100:101]
	global_load_dword v28, v[4:5], off
	v_lshl_add_u64 v[4:5], v[2:3], 0, v[102:103]
	global_load_dword v29, v[4:5], off
	v_lshl_add_u64 v[4:5], v[2:3], 0, v[104:105]
	global_load_dword v30, v[4:5], off
	v_lshl_add_u64 v[4:5], v[2:3], 0, v[106:107]
	global_load_dword v31, v[4:5], off
	v_lshl_add_u64 v[4:5], v[2:3], 0, v[108:109]
	global_load_dword v32, v[4:5], off
	v_lshl_add_u64 v[4:5], v[2:3], 0, v[110:111]
	global_load_dword v33, v[4:5], off
	v_lshl_add_u64 v[4:5], v[2:3], 0, v[112:113]
	global_load_dword v34, v[4:5], off
	v_lshl_add_u64 v[4:5], v[2:3], 0, v[114:115]
	global_load_dword v35, v[4:5], off
	v_lshl_add_u64 v[4:5], v[2:3], 0, v[116:117]
	v_lshl_add_u64 v[2:3], v[2:3], 0, v[120:121]
	global_load_dword v36, v[4:5], off
	global_load_dword v37, v[2:3], off
	v_add_u32_e32 v6, v182, v185
	s_waitcnt vmcnt(15)
	ds_write_b32 v6, v22
	s_waitcnt vmcnt(14)
	ds_write_b32 v6, v23 offset:1040
	s_waitcnt vmcnt(13)
	ds_write_b32 v6, v24 offset:2080
	s_waitcnt vmcnt(12)
	ds_write_b32 v6, v25 offset:3120
	s_waitcnt vmcnt(11)
	ds_write_b32 v6, v26 offset:4160
	s_waitcnt vmcnt(10)
	ds_write_b32 v6, v27 offset:5200
	v_add_u32_e32 v6, v182, v186
	s_waitcnt vmcnt(9)
	ds_write_b32 v6, v28
	s_waitcnt vmcnt(8)
	ds_write_b32 v6, v29 offset:1040
	s_waitcnt vmcnt(7)
	ds_write_b32 v6, v30 offset:2080
	s_waitcnt vmcnt(6)
	ds_write_b32 v6, v31 offset:3120
	s_waitcnt vmcnt(5)
	ds_write_b32 v6, v32 offset:4160
	s_waitcnt vmcnt(4)
	ds_write_b32 v6, v33 offset:5200
	s_waitcnt vmcnt(3)
	ds_write_b32 v6, v34 offset:6240
	s_waitcnt vmcnt(2)
	ds_write_b32 v6, v35 offset:7280
	s_waitcnt vmcnt(1)
	ds_write_b32 v6, v36 offset:8320
	s_waitcnt vmcnt(0)
	ds_write_b32 v6, v37 offset:9360
	s_waitcnt lgkmcnt(0)
	s_barrier
; __device__ __forceinline__ unsigned pack2(float a, float b) { return (unsigned)f2bf(a) | ((unsigned)f2bf(b) << 16); }
; __device__ void transpose_job64(int tid_, int bid_, int nblk_, const float* __restrict__ src, u16* __restrict__ dst, int K, int N,
;                                 int nbatch, size_t sstride, size_t dstride, int ldd, float* sm) {
;     ...
;     {
;       int n = tid >> 2, kc = tid & 3;
;       unsigned o[8];
; #pragma unroll
;       for (int e = 0; e < 8; ++e) o[e] = pack2(sm[(kc * 16 + 2 * e) * 65 + n], sm[(kc * 16 + 2 * e + 1) * 65 + n]);
;       u16* d = dst + (size_t)bi * dstride + (size_t)(nt * 64 + n) * ldd + kt * 64 + kc * 16;
;       *(uint4*)(d) = make_uint4(o[0], o[1], o[2], o[3]);
;       *(uint4*)(d + 8) = make_uint4(o[4], o[5], o[6], o[7]);
;     }
;     __syncthreads();
	ds_read2_b32 v[2:3], v184 offset1:65
	ds_read2_b32 v[4:5], v184 offset0:130 offset1:195
	v_add_u32_e32 v1, 0x400, v184
	ds_read2_b32 v[6:7], v1 offset0:4 offset1:69
	ds_read2_b32 v[8:9], v1 offset0:134 offset1:199
	v_add_u32_e32 v1, 0x800, v184
	ds_read2_b32 v[10:11], v1 offset0:8 offset1:73
	ds_read2_b32 v[12:13], v1 offset0:138 offset1:203
	v_add_u32_e32 v1, 0xc00, v184
	ds_read2_b32 v[14:15], v1 offset0:12 offset1:77
	ds_read2_b32 v[16:17], v1 offset0:142 offset1:207
	s_waitcnt lgkmcnt(6)
	v_and_b32_sdwa v1, v4, v198 dst_sel:DWORD dst_unused:UNUSED_PAD src0_sel:WORD_1 src1_sel:DWORD
	v_and_b32_sdwa v20, v2, v198 dst_sel:DWORD dst_unused:UNUSED_PAD src0_sel:WORD_1 src1_sel:DWORD
	v_add3_u32 v1, v4, v1, s63
	v_and_b32_sdwa v4, v5, v198 dst_sel:DWORD dst_unused:UNUSED_PAD src0_sel:WORD_1 src1_sel:DWORD
	v_add3_u32 v2, v2, v20, s63
	v_and_b32_sdwa v20, v3, v198 dst_sel:DWORD dst_unused:UNUSED_PAD src0_sel:WORD_1 src1_sel:DWORD
	v_add3_u32 v4, v5, v4, s63
	v_add3_u32 v3, v3, v20, s63
	v_and_b32_e32 v4, 0xffff0000, v4
	v_and_b32_e32 v5, 0xffff0000, v3
	v_or_b32_sdwa v3, v4, v1 dst_sel:DWORD dst_unused:UNUSED_PAD src0_sel:DWORD src1_sel:WORD_1
	s_waitcnt lgkmcnt(5)
	v_and_b32_sdwa v4, v6, v198 dst_sel:DWORD dst_unused:UNUSED_PAD src0_sel:WORD_1 src1_sel:DWORD
	v_or_b32_sdwa v2, v5, v2 dst_sel:DWORD dst_unused:UNUSED_PAD src0_sel:DWORD src1_sel:WORD_1
	v_add3_u32 v4, v6, v4, s63
	s_waitcnt lgkmcnt(4)
	v_and_b32_sdwa v5, v9, v198 dst_sel:DWORD dst_unused:UNUSED_PAD src0_sel:WORD_1 src1_sel:DWORD
	v_and_b32_sdwa v6, v7, v198 dst_sel:DWORD dst_unused:UNUSED_PAD src0_sel:WORD_1 src1_sel:DWORD
	v_and_b32_sdwa v1, v8, v198 dst_sel:DWORD dst_unused:UNUSED_PAD src0_sel:WORD_1 src1_sel:DWORD
	v_add3_u32 v5, v9, v5, s63
	v_add3_u32 v6, v7, v6, s63
	v_add3_u32 v1, v8, v1, s63
	v_and_b32_e32 v5, 0xffff0000, v5
	v_and_b32_e32 v6, 0xffff0000, v6
	v_or_b32_sdwa v5, v5, v1 dst_sel:DWORD dst_unused:UNUSED_PAD src0_sel:DWORD src1_sel:WORD_1
	v_or_b32_sdwa v4, v6, v4 dst_sel:DWORD dst_unused:UNUSED_PAD src0_sel:DWORD src1_sel:WORD_1
	global_store_dwordx4 v[18:19], v[2:5], off
	s_waitcnt lgkmcnt(2)
	v_and_b32_sdwa v1, v12, v198 dst_sel:DWORD dst_unused:UNUSED_PAD src0_sel:WORD_1 src1_sel:DWORD
	v_add3_u32 v1, v12, v1, s63
	v_and_b32_sdwa v3, v13, v198 dst_sel:DWORD dst_unused:UNUSED_PAD src0_sel:WORD_1 src1_sel:DWORD
	v_and_b32_sdwa v4, v11, v198 dst_sel:DWORD dst_unused:UNUSED_PAD src0_sel:WORD_1 src1_sel:DWORD
	v_and_b32_sdwa v2, v10, v198 dst_sel:DWORD dst_unused:UNUSED_PAD src0_sel:WORD_1 src1_sel:DWORD
	v_add3_u32 v3, v13, v3, s63
	v_add3_u32 v4, v11, v4, s63
	v_add3_u32 v2, v10, v2, s63
	v_and_b32_e32 v3, 0xffff0000, v3
	v_and_b32_e32 v4, 0xffff0000, v4
	s_waitcnt lgkmcnt(0)
	v_and_b32_sdwa v5, v17, v198 dst_sel:DWORD dst_unused:UNUSED_PAD src0_sel:WORD_1 src1_sel:DWORD
	v_and_b32_sdwa v6, v15, v198 dst_sel:DWORD dst_unused:UNUSED_PAD src0_sel:WORD_1 src1_sel:DWORD
	v_or_b32_sdwa v3, v3, v1 dst_sel:DWORD dst_unused:UNUSED_PAD src0_sel:DWORD src1_sel:WORD_1
	v_or_b32_sdwa v2, v4, v2 dst_sel:DWORD dst_unused:UNUSED_PAD src0_sel:DWORD src1_sel:WORD_1
	v_and_b32_sdwa v1, v16, v198 dst_sel:DWORD dst_unused:UNUSED_PAD src0_sel:WORD_1 src1_sel:DWORD
	v_and_b32_sdwa v4, v14, v198 dst_sel:DWORD dst_unused:UNUSED_PAD src0_sel:WORD_1 src1_sel:DWORD
	v_add3_u32 v5, v17, v5, s63
	v_add3_u32 v6, v15, v6, s63
	v_add3_u32 v4, v14, v4, s63
	v_add3_u32 v1, v16, v1, s63
	v_and_b32_e32 v5, 0xffff0000, v5
	v_and_b32_e32 v6, 0xffff0000, v6
	v_or_b32_sdwa v5, v5, v1 dst_sel:DWORD dst_unused:UNUSED_PAD src0_sel:DWORD src1_sel:WORD_1
	v_or_b32_sdwa v4, v6, v4 dst_sel:DWORD dst_unused:UNUSED_PAD src0_sel:DWORD src1_sel:WORD_1
	global_store_dwordx4 v[18:19], v[2:5], off offset:16
	s_barrier
	s_cbranch_scc0 .LBB0_620
	s_mov_b64 s[20:21], 0

; __device__ void transpose_job64(int tid_, int bid_, int nblk_, const float* __restrict__ src, u16* __restrict__ dst, int K, int N,
;                                 int nbatch, size_t sstride, size_t dstride, int ldd, float* sm) {
;     ...
;   for (int t = bid_; t < total; t += nblk_) {
;     int bi = t / per, r = t % per, kt = r / tn, nt = r % tn;
;     const float* s = src + (size_t)bi * sstride + (size_t)(kt * 64) * N + nt * 64;
; #pragma unroll
;     for (int i = 0; i < 16; ++i) {
;       int kk = (tid >> 6) + 4 * i, nn = tid & 63;
;       sm[kk * 65 + nn] = s[(size_t)kk * N + nn];
;     }
;     __syncthreads();
; __device__ void mix_phase(int tid_, int bid_, int nblk_, const Params& p, int li, char* smem) {
;     ...
;     if (j < 128) { transpose_job64(tid_, j, 128, p.ev_w_out, p.wt_ev_out, 2048, 2048, 2, (size_t)2048 * 2048, (size_t)2048 * 2048, 2048, sm); continue; }
.LBB0_625:
	s_ashr_i32 s20, s0, 31
	s_lshr_b32 s20, s20, 22
	s_add_i32 s21, s0, s20
	s_ashr_i32 s20, s21, 10
	s_and_b32 s21, s21, 0xfc00
	s_sub_i32 s21, s0, s21
	s_sext_i32_i16 s22, s21
	s_bfe_u32 s22, s22, 0x5001a
	s_add_i32 s22, s21, s22
	s_sext_i32_i16 s24, s22
	s_and_b32 s22, s22, 0xffe0
	s_sub_i32 s21, s21, s22
	s_sext_i32_i16 s26, s21
	s_ashr_i32 s21, s20, 31
	s_lshl_b64 s[22:23], s[20:21], 24
	s_add_u32 s27, s44, s22
	s_addc_u32 s28, s45, s23
	s_lshl_b32 s22, s24, 1
	s_andn2_b32 s22, s22, 63
	s_ashr_i32 s23, s22, 31
	s_lshl_b64 s[24:25], s[22:23], 13
	s_add_u32 s29, s27, s24
	s_addc_u32 s28, s28, s25
	s_lshl_b32 s24, s26, 6
	s_ashr_i32 s25, s24, 31
	s_lshl_b64 s[26:27], s[24:25], 2
	s_add_u32 s26, s29, s26
	s_addc_u32 s27, s28, s27
	v_lshlrev_b32_e32 v2, 2, v52
	v_mov_b32_e32 v3, v0
	v_lshl_add_u64 v[2:3], s[26:27], 0, v[2:3]
	v_lshl_add_u64 v[4:5], v[2:3], 0, v[56:57]
	global_load_dword v22, v[4:5], off
	v_lshl_add_u64 v[4:5], v[2:3], 0, v[58:59]
	s_lshl_b64 s[20:21], s[20:21], 23
	v_add_u32_e32 v18, s24, v183
	s_add_u32 s20, s4, s20
	v_ashrrev_i32_e32 v19, 31, v18
	s_addc_u32 s21, s5, s21
	v_lshlrev_b64 v[18:19], 12, v[18:19]
	v_lshl_add_u64 v[18:19], s[20:21], 0, v[18:19]
	v_lshl_add_u64 v[18:19], s[22:23], 1, v[18:19]
	v_lshlrev_b32_e32 v20, 1, v54
	v_mov_b32_e32 v21, v0
	v_lshl_add_u64 v[18:19], v[18:19], 0, v[20:21]
	s_add_i32 s20, s0, 0x80
	s_cmpk_gt_i32 s0, 0x77f
	s_mov_b32 s0, s20
	global_load_dword v23, v[4:5], off
	v_lshl_add_u64 v[4:5], v[2:3], 0, v[60:61]
	global_load_dword v24, v[4:5], off
	v_lshl_add_u64 v[4:5], v[2:3], 0, v[62:63]
	global_load_dword v25, v[4:5], off
	v_lshl_add_u64 v[4:5], v[2:3], 0, v[64:65]
	global_load_dword v26, v[4:5], off
	v_lshl_add_u64 v[4:5], v[2:3], 0, v[66:67]
	global_load_dword v27, v[4:5], off
	v_lshl_add_u64 v[4:5], v[2:3], 0, v[68:69]
	global_load_dword v28, v[4:5], off
	v_lshl_add_u64 v[4:5], v[2:3], 0, v[70:71]
	global_load_dword v29, v[4:5], off
	v_lshl_add_u64 v[4:5], v[2:3], 0, v[72:73]
	global_load_dword v30, v[4:5], off
	v_lshl_add_u64 v[4:5], v[2:3], 0, v[74:75]
	global_load_dword v31, v[4:5], off
	v_lshl_add_u64 v[4:5], v[2:3], 0, v[76:77]
	global_load_dword v32, v[4:5], off
	v_lshl_add_u64 v[4:5], v[2:3], 0, v[78:79]
	global_load_dword v33, v[4:5], off
	v_lshl_add_u64 v[4:5], v[2:3], 0, v[80:81]
	global_load_dword v34, v[4:5], off
	v_lshl_add_u64 v[4:5], v[2:3], 0, v[82:83]
	global_load_dword v35, v[4:5], off
	v_lshl_add_u64 v[4:5], v[2:3], 0, v[84:85]
	v_lshl_add_u64 v[2:3], v[2:3], 0, v[86:87]
	global_load_dword v36, v[4:5], off
	global_load_dword v37, v[2:3], off
	v_add_u32_e32 v6, v182, v185
	s_waitcnt vmcnt(15)
	ds_write_b32 v6, v22
	s_waitcnt vmcnt(14)
	ds_write_b32 v6, v23 offset:1040
	s_waitcnt vmcnt(13)
	ds_write_b32 v6, v24 offset:2080
	s_waitcnt vmcnt(12)
	ds_write_b32 v6, v25 offset:3120
	s_waitcnt vmcnt(11)
	ds_write_b32 v6, v26 offset:4160
	s_waitcnt vmcnt(10)
	ds_write_b32 v6, v27 offset:5200
	v_add_u32_e32 v6, v182, v186
	s_waitcnt vmcnt(9)
	ds_write_b32 v6, v28
	s_waitcnt vmcnt(8)
	ds_write_b32 v6, v29 offset:1040
	s_waitcnt vmcnt(7)
	ds_write_b32 v6, v30 offset:2080
	s_waitcnt vmcnt(6)
	ds_write_b32 v6, v31 offset:3120
	s_waitcnt vmcnt(5)
	ds_write_b32 v6, v32 offset:4160
	s_waitcnt vmcnt(4)
	ds_write_b32 v6, v33 offset:5200
	s_waitcnt vmcnt(3)
	ds_write_b32 v6, v34 offset:6240
	s_waitcnt vmcnt(2)
	ds_write_b32 v6, v35 offset:7280
	s_waitcnt vmcnt(1)
	ds_write_b32 v6, v36 offset:8320
	s_waitcnt vmcnt(0)
	ds_write_b32 v6, v37 offset:9360
	s_waitcnt lgkmcnt(0)
	s_barrier
; __device__ __forceinline__ unsigned pack2(float a, float b) { return (unsigned)f2bf(a) | ((unsigned)f2bf(b) << 16); }
; __device__ void transpose_job64(int tid_, int bid_, int nblk_, const float* __restrict__ src, u16* __restrict__ dst, int K, int N,
;                                 int nbatch, size_t sstride, size_t dstride, int ldd, float* sm) {
;     ...
;     {
;       int n = tid >> 2, kc = tid & 3;
;       unsigned o[8];
; #pragma unroll
;       for (int e = 0; e < 8; ++e) o[e] = pack2(sm[(kc * 16 + 2 * e) * 65 + n], sm[(kc * 16 + 2 * e + 1) * 65 + n]);
;       u16* d = dst + (size_t)bi * dstride + (size_t)(nt * 64 + n) * ldd + kt * 64 + kc * 16;
;       *(uint4*)(d) = make_uint4(o[0], o[1], o[2], o[3]);
;       *(uint4*)(d + 8) = make_uint4(o[4], o[5], o[6], o[7]);
;     }
;     __syncthreads();
	ds_read2_b32 v[2:3], v184 offset1:65
	ds_read2_b32 v[4:5], v184 offset0:130 offset1:195
	v_add_u32_e32 v1, 0x400, v184
	ds_read2_b32 v[6:7], v1 offset0:4 offset1:69
	ds_read2_b32 v[8:9], v1 offset0:134 offset1:199
	v_add_u32_e32 v1, 0x800, v184
	ds_read2_b32 v[10:11], v1 offset0:8 offset1:73
	ds_read2_b32 v[12:13], v1 offset0:138 offset1:203
	v_add_u32_e32 v1, 0xc00, v184
	ds_read2_b32 v[14:15], v1 offset0:12 offset1:77
	ds_read2_b32 v[16:17], v1 offset0:142 offset1:207
	s_waitcnt lgkmcnt(6)
	v_and_b32_sdwa v1, v4, v198 dst_sel:DWORD dst_unused:UNUSED_PAD src0_sel:WORD_1 src1_sel:DWORD
	v_and_b32_sdwa v20, v2, v198 dst_sel:DWORD dst_unused:UNUSED_PAD src0_sel:WORD_1 src1_sel:DWORD
	v_add3_u32 v1, v4, v1, s63
	v_and_b32_sdwa v4, v5, v198 dst_sel:DWORD dst_unused:UNUSED_PAD src0_sel:WORD_1 src1_sel:DWORD
	v_add3_u32 v2, v2, v20, s63
	v_and_b32_sdwa v20, v3, v198 dst_sel:DWORD dst_unused:UNUSED_PAD src0_sel:WORD_1 src1_sel:DWORD
	v_add3_u32 v4, v5, v4, s63
	v_add3_u32 v3, v3, v20, s63
	v_and_b32_e32 v4, 0xffff0000, v4
	v_and_b32_e32 v5, 0xffff0000, v3
	v_or_b32_sdwa v3, v4, v1 dst_sel:DWORD dst_unused:UNUSED_PAD src0_sel:DWORD src1_sel:WORD_1
	s_waitcnt lgkmcnt(5)
	v_and_b32_sdwa v4, v6, v198 dst_sel:DWORD dst_unused:UNUSED_PAD src0_sel:WORD_1 src1_sel:DWORD
	v_or_b32_sdwa v2, v5, v2 dst_sel:DWORD dst_unused:UNUSED_PAD src0_sel:DWORD src1_sel:WORD_1
	v_add3_u32 v4, v6, v4, s63
	s_waitcnt lgkmcnt(4)
	v_and_b32_sdwa v5, v9, v198 dst_sel:DWORD dst_unused:UNUSED_PAD src0_sel:WORD_1 src1_sel:DWORD
	v_and_b32_sdwa v6, v7, v198 dst_sel:DWORD dst_unused:UNUSED_PAD src0_sel:WORD_1 src1_sel:DWORD
	v_and_b32_sdwa v1, v8, v198 dst_sel:DWORD dst_unused:UNUSED_PAD src0_sel:WORD_1 src1_sel:DWORD
	v_add3_u32 v5, v9, v5, s63
	v_add3_u32 v6, v7, v6, s63
	v_add3_u32 v1, v8, v1, s63
	v_and_b32_e32 v5, 0xffff0000, v5
	v_and_b32_e32 v6, 0xffff0000, v6
	v_or_b32_sdwa v5, v5, v1 dst_sel:DWORD dst_unused:UNUSED_PAD src0_sel:DWORD src1_sel:WORD_1
	v_or_b32_sdwa v4, v6, v4 dst_sel:DWORD dst_unused:UNUSED_PAD src0_sel:DWORD src1_sel:WORD_1
	global_store_dwordx4 v[18:19], v[2:5], off
	s_waitcnt lgkmcnt(2)
	v_and_b32_sdwa v1, v12, v198 dst_sel:DWORD dst_unused:UNUSED_PAD src0_sel:WORD_1 src1_sel:DWORD
	v_add3_u32 v1, v12, v1, s63
	v_and_b32_sdwa v3, v13, v198 dst_sel:DWORD dst_unused:UNUSED_PAD src0_sel:WORD_1 src1_sel:DWORD
	v_and_b32_sdwa v4, v11, v198 dst_sel:DWORD dst_unused:UNUSED_PAD src0_sel:WORD_1 src1_sel:DWORD
	v_and_b32_sdwa v2, v10, v198 dst_sel:DWORD dst_unused:UNUSED_PAD src0_sel:WORD_1 src1_sel:DWORD
	v_add3_u32 v3, v13, v3, s63
	v_add3_u32 v4, v11, v4, s63
	v_add3_u32 v2, v10, v2, s63
	v_and_b32_e32 v3, 0xffff0000, v3
	v_and_b32_e32 v4, 0xffff0000, v4
	s_waitcnt lgkmcnt(0)
	v_and_b32_sdwa v5, v17, v198 dst_sel:DWORD dst_unused:UNUSED_PAD src0_sel:WORD_1 src1_sel:DWORD
	v_and_b32_sdwa v6, v15, v198 dst_sel:DWORD dst_unused:UNUSED_PAD src0_sel:WORD_1 src1_sel:DWORD
	v_or_b32_sdwa v3, v3, v1 dst_sel:DWORD dst_unused:UNUSED_PAD src0_sel:DWORD src1_sel:WORD_1
	v_or_b32_sdwa v2, v4, v2 dst_sel:DWORD dst_unused:UNUSED_PAD src0_sel:DWORD src1_sel:WORD_1
	v_and_b32_sdwa v1, v16, v198 dst_sel:DWORD dst_unused:UNUSED_PAD src0_sel:WORD_1 src1_sel:DWORD
	v_and_b32_sdwa v4, v14, v198 dst_sel:DWORD dst_unused:UNUSED_PAD src0_sel:WORD_1 src1_sel:DWORD
	v_add3_u32 v5, v17, v5, s63
	v_add3_u32 v6, v15, v6, s63
	v_add3_u32 v4, v14, v4, s63
	v_add3_u32 v1, v16, v1, s63
	v_and_b32_e32 v5, 0xffff0000, v5
	v_and_b32_e32 v6, 0xffff0000, v6
	v_or_b32_sdwa v5, v5, v1 dst_sel:DWORD dst_unused:UNUSED_PAD src0_sel:DWORD src1_sel:WORD_1
	v_or_b32_sdwa v4, v6, v4 dst_sel:DWORD dst_unused:UNUSED_PAD src0_sel:DWORD src1_sel:WORD_1
	global_store_dwordx4 v[18:19], v[2:5], off offset:16
	s_barrier
	s_cbranch_scc0 .LBB0_625
	s_mov_b64 s[20:21], 0
